# final_norm rows remapped to the XCD that owns their M-tiles + XCD-local seam G7->final_norm
# baseline (speedup 1.0000x reference)
.LBB0_3402:
	s_cmp_lt_i32 s42, 25
	s_cselect_b64 s[0:1], -1, 0
	s_cmp_gt_i32 s43, 24
	s_cselect_b64 s[2:3], -1, 0
	s_and_b64 s[0:1], s[0:1], s[2:3]
	s_andn2_b64 vcc, exec, s[0:1]
	s_cbranch_vccnz .LBB0_3460
	v_mbcnt_hi_u32_b32 v0, -1, v210
	v_add_u32_e32 v0, s91, v0
	s_waitcnt lgkmcnt(0)
	s_load_dword s10, s[88:89], 0x160
	s_add_u32 s4, s88, 0x160
	v_readfirstlane_b32 s1, v0
	s_addc_u32 s5, s89, 0
	s_ashr_i32 s1, s1, 6
	s_waitcnt lgkmcnt(0)
	s_mov_b32 s0, s10
	s_and_b32 s2, s90, 7
	s_lshl_b32 s2, s2, 11
	s_add_i32 s16, s2, 0x800
	s_lshr_b32 s3, s90, 3
	s_lshl_b32 s3, s3, 3
	s_add_i32 s2, s2, s3
	s_add_i32 s11, s1, s2
	s_cmpk_gt_i32 s11, 0x3fff
	s_cbranch_scc1 .LBB0_3406
	s_load_dwordx4 s[12:15], s[88:89], 0x140
	s_load_dwordx2 s[6:7], s[88:89], 0x150
	s_movk_i32 s0, 0x100
	s_ashr_i32 s3, s1, 31
	s_ashr_i32 s9, s2, 31
	s_add_u32 s8, s1, s2
	s_addc_u32 s9, s3, s9
	s_lshl_b64 s[2:3], s[8:9], 6
	s_waitcnt lgkmcnt(0)
	s_add_u32 s1, s6, s2
	s_addc_u32 s3, s7, s3
	s_add_u32 s2, s1, 0x100000
	s_addc_u32 s3, s3, 0
	s_ashr_i32 s1, s0, 31
	s_lshl_b64 s[6:7], s[0:1], 6
	s_lshl_b64 s[8:9], s[8:9], 12
	v_and_b32_e32 v0, 63, v0
	s_add_u32 s8, s14, s8
	v_lshlrev_b32_e32 v0, 4, v0
	v_mov_b32_e32 v1, 0
	s_addc_u32 s9, s15, s9
	v_lshl_add_u64 v[4:5], s[8:9], 0, v[0:1]
	s_mov_b64 s[8:9], 0x800
	v_lshl_add_u64 v[2:3], s[12:13], 0, v[0:1]
	v_lshl_add_u64 v[4:5], v[4:5], 0, s[8:9]
	s_lshl_b64 s[8:9], s[0:1], 12
	v_mov_b32_e32 v0, 0x358637bd
	s_mov_b32 s1, 0x800000
.LBB0_3405:
	global_load_dwordx4 v[6:9], v1, s[2:3]
	global_load_dwordx4 v[10:13], v1, s[2:3] offset:16
	global_load_dwordx4 v[14:17], v1, s[2:3] offset:32
	global_load_dwordx4 v[18:21], v1, s[2:3] offset:48
	global_load_dwordx4 v[22:25], v[4:5], off offset:-2048
	global_load_dwordx4 v[26:29], v[2:3], off
	global_load_dwordx4 v[30:33], v[4:5], off offset:-1024
	s_add_i32 s11, s11, s0
	s_add_u32 s2, s2, s6
	s_addc_u32 s3, s3, s7
	s_cmp_lt_i32 s11, s16
	s_waitcnt vmcnt(6)
	v_mov_b32_e32 v34, v7
	v_mov_b32_e32 v35, v8
	v_mov_b32_e32 v7, v9
	s_waitcnt vmcnt(5)
	v_mov_b32_e32 v8, v11
	v_mov_b32_e32 v9, v12
	v_mov_b32_e32 v11, v13
	v_pk_add_f32 v[6:7], v[34:35], v[6:7]
	v_pk_add_f32 v[8:9], v[8:9], v[10:11]
	v_pk_add_f32 v[6:7], v[6:7], v[6:7] op_sel:[0,1] op_sel_hi:[1,0]
	v_pk_add_f32 v[8:9], v[8:9], v[8:9] op_sel:[0,1] op_sel_hi:[1,0]
	s_waitcnt vmcnt(4)
	v_add_f32_e32 v12, v14, v15
	v_add_f32_e32 v14, v16, v17
	s_waitcnt vmcnt(3)
	v_mov_b32_e32 v13, v20
	v_mov_b32_e32 v15, v21
	v_mov_b32_e32 v7, v18
	v_mov_b32_e32 v9, v19
	v_pk_add_f32 v[10:11], v[12:13], v[14:15]
	v_pk_add_f32 v[6:7], v[6:7], v[8:9]
	s_nop 0
	v_pk_add_f32 v[6:7], v[6:7], v[10:11]
	s_nop 0
	v_add_f32_e32 v6, v6, v7
	v_fmamk_f32 v6, v6, 0x3a800000, v0
	v_mul_f32_e32 v7, 0x4b800000, v6
	v_cmp_gt_f32_e32 vcc, s1, v6
	s_nop 1
	v_cndmask_b32_e32 v6, v6, v7, vcc
	v_rsq_f32_e32 v6, v6
	s_nop 0
	v_mul_f32_e32 v7, 0x45800000, v6
	v_cndmask_b32_e32 v18, v6, v7, vcc
	s_waitcnt vmcnt(2)
	v_pk_mul_f32 v[6:7], v[22:23], v[18:19] op_sel_hi:[1,0]
	v_pk_mul_f32 v[8:9], v[24:25], v[18:19] op_sel_hi:[1,0]
	s_waitcnt vmcnt(1)
	v_pk_mul_f32 v[6:7], v[26:27], v[6:7]
	v_pk_mul_f32 v[8:9], v[28:29], v[8:9]
	global_store_dwordx4 v[4:5], v[6:9], off offset:-2048
	global_load_dwordx4 v[6:9], v[2:3], off offset:1024
	s_nop 0
	global_load_dwordx4 v[10:13], v[4:5], off
	s_waitcnt vmcnt(3)
	v_pk_mul_f32 v[14:15], v[32:33], v[18:19] op_sel_hi:[1,0]
	v_pk_mul_f32 v[16:17], v[30:31], v[18:19] op_sel_hi:[1,0]
	s_waitcnt vmcnt(1)
	v_pk_mul_f32 v[8:9], v[8:9], v[14:15]
	v_pk_mul_f32 v[6:7], v[6:7], v[16:17]
	global_store_dwordx4 v[4:5], v[6:9], off offset:-1024
	global_load_dwordx4 v[6:9], v[2:3], off offset:2048
	s_nop 0
	global_load_dwordx4 v[14:17], v[4:5], off offset:1024
	s_waitcnt vmcnt(3)
	v_pk_mul_f32 v[12:13], v[12:13], v[18:19] op_sel_hi:[1,0]
	v_pk_mul_f32 v[10:11], v[10:11], v[18:19] op_sel_hi:[1,0]
	s_waitcnt vmcnt(1)
	v_pk_mul_f32 v[8:9], v[8:9], v[12:13]
	v_pk_mul_f32 v[6:7], v[6:7], v[10:11]
	global_store_dwordx4 v[4:5], v[6:9], off
	global_load_dwordx4 v[6:9], v[2:3], off offset:3072
	s_waitcnt vmcnt(2)
	v_pk_mul_f32 v[10:11], v[16:17], v[18:19] op_sel_hi:[1,0]
	v_pk_mul_f32 v[12:13], v[14:15], v[18:19] op_sel_hi:[1,0]
	s_waitcnt vmcnt(0)
	v_pk_mul_f32 v[8:9], v[8:9], v[10:11]
	v_pk_mul_f32 v[6:7], v[6:7], v[12:13]
	global_store_dwordx4 v[4:5], v[6:9], off offset:1024
	v_lshl_add_u64 v[4:5], v[4:5], 0, s[8:9]
	s_cbranch_scc1 .LBB0_3405
